# top-k rank via 64-bit order-preserving keys (value bits + inverted lane index): 2 DPP rotations + one v_cmp_gt_u64 + one addc per step, no SALU mask ops
# speedup vs baseline: 1.0260x; 1.0063x over previous
.LBB0_115:
	v_add_u32_e32 v38, s4, v34
	v_and_or_b32 v39, v38, 31, v35
	v_lshl_add_u32 v39, v39, 8, v36
	ds_read2st64_b32 v[40:41], v39 offset1:64
	s_mov_b32 s5, 0
	s_waitcnt lgkmcnt(0)
	v_add_f32_e32 v40, 0, v40
	v_add_f32_e32 v42, v40, v41
	ds_read2st64_b32 v[40:41], v39 offset0:128 offset1:192
	s_waitcnt lgkmcnt(0)
	v_add_f32_e32 v39, v42, v40
	v_add_f32_e32 v39, v39, v41
	v_mov_b32_e32 v40, 0xce6e6b28
	v_cndmask_b32_e64 v39, v39, v40, s[12:13]
	v_mov_b32_e32 v40, 0x4e6e6b28
	v_cndmask_b32_e64 v39, v39, v40, s[10:11]
	v_mov_b32_e32 v41, 0
	v_mov_b32_e32 v40, v37
	v_ashrrev_i32_e32 v43, 31, v39
	v_or_b32_e32 v43, 0x80000000, v43
	v_xor_b32_e32 v43, v39, v43
	v_sub_u32_e32 v44, 63, v217
	v_lshl_or_b32 v44, v43, 6, v44
	v_lshrrev_b32_e32 v45, 26, v43
	v_mov_b32_e32 v46, v44
	v_mov_b32_e32 v47, v45
	s_nop 1
	v_mov_b32_dpp v46, v46 wave_ror:1 row_mask:0xf bank_mask:0xf
	v_mov_b32_dpp v47, v47 wave_ror:1 row_mask:0xf bank_mask:0xf
	v_cmp_gt_u64_e64 s[16:17], v[46:47], v[44:45]
.LBB0_116:
	v_mov_b32_dpp v46, v46 wave_ror:1 row_mask:0xf bank_mask:0xf
	v_mov_b32_dpp v47, v47 wave_ror:1 row_mask:0xf bank_mask:0xf
	v_addc_co_u32_e64 v41, s[16:17], 0, v41, s[16:17]
	v_cmp_gt_u64_e64 s[16:17], v[46:47], v[44:45]
	v_mov_b32_dpp v46, v46 wave_ror:1 row_mask:0xf bank_mask:0xf
	v_mov_b32_dpp v47, v47 wave_ror:1 row_mask:0xf bank_mask:0xf
	v_addc_co_u32_e64 v41, s[16:17], 0, v41, s[16:17]
	v_cmp_gt_u64_e64 s[16:17], v[46:47], v[44:45]
	s_add_i32 s5, s5, 1
	s_cmp_eq_u32 s5, 31
	s_cbranch_scc0 .LBB0_116
	s_nop 1
	v_addc_co_u32_e64 v41, s[16:17], 0, v41, s[16:17]
	s_branch .Lmy_rank_done
	s_nop 0
	s_nop 0
	s_nop 0
	s_nop 0
	s_nop 0
	s_nop 0
	s_nop 0
	s_nop 0
	s_nop 0
	s_nop 0
	s_nop 0
	s_nop 0
	s_nop 0
	s_nop 0
	s_nop 0
	s_nop 0
	s_nop 0
	s_nop 0
	s_nop 0
	s_nop 0
	s_nop 0
	s_nop 0
	s_nop 0
	s_nop 0
	s_nop 0
	s_nop 0
	s_nop 0
	s_nop 0
	s_nop 0
	s_nop 0
	s_nop 0
	s_nop 0
	s_nop 0
	s_nop 0
	s_nop 0
	s_nop 0
	s_nop 0
	s_nop 0
	s_nop 0
	s_nop 0
	s_nop 0
	s_nop 0
	s_nop 0
	s_nop 0
	s_nop 0
	s_nop 0
	s_nop 0
	s_nop 0
	s_nop 0
	s_nop 0
	s_nop 0
	s_nop 0
	s_nop 0
	s_nop 0
